# down-proj: the 4-way split sample-panel units now run FIRST on CUs 0-63 (under full-load latency) instead of last in the shadow of the PLE-projection GEMM
# baseline (speedup 1.0000x reference)
;     __device__ __forceinline__ bool next(int i, Unit& u) const {
;         constexpr int NU = (33792 / BM) * NN;
;         const int L = i * G + ((NU - i * G < G) ? vp : v); if (L >= NU) return false;
;         constexpr int NM = 33792 / BM, NFULL = (NM / 8) * 8 * NN;
;         if (L < NFULL) { const int g = L / (8 * NN), idx = L % (8 * NN); u.pm = g * 8 + (idx & 7); u.pn = idx >> 3; }
;         else { constexpr int GS = NM % 8 ? NM % 8 : 8; const int idx = L - NFULL; u.pm = (NM / 8) * 8 + idx % GS; u.pn = idx / GS; }
.LBB0_643:
	v_readlane_b32 s2, v249, 17
	v_readlane_b32 s3, v249, 18
	s_and_b64 s[2:3], s[2:3], exec
	s_cselect_b32 s2, s0, s1
	s_cmp_lg_u32 s64, 0x100
	s_cbranch_scc1 .Lp5a_f
	s_cmp_gt_u32 s86, 63
	s_cbranch_scc1 .Lp5a_f
	s_and_b32 s7, s86, 7
	s_lshl_b32 s7, s7, 1
	s_bfe_u32 s2, s86, 0x10005
	s_add_i32 s2, s2, s7
	s_addk_i32 s2, 0x200
.Lp5a_f:
	v_mov_b32_e32 v0, v196
	s_cmpk_gt_i32 s2, 0x20f
	s_cbranch_scc0 .LBB0_650
	s_and_b64 vcc, exec, s[74:75]
	s_mov_b32 s1, s86
	s_cbranch_vccz .LBB0_678

; #define PG8_STAGE(bufoff, gbase, voff) do { _Pragma("unroll") for (int _i = 0; _i < 2; ++_i) \
;         __builtin_amdgcn_global_load_lds((const unsigned*)((const char*)(gbase) + (voff)[_i]), (LAS unsigned*)(lds + (bufoff) + ldsw + _i * 8192), 16, 0, 0); } while (0)
; template <int KK, class Epi, class Sched, bool ALIGN_EPI = true>
; __device__ __forceinline__ void gemm_phase(LAS unsigned char* lds, const bf16* gA, const bf16* gBt, const Sched& S, const Epi& E, const int wid) {
;     ...
;     unsigned voffA[2], voffB[2];
; #pragma unroll
;     for (int i = 0; i < 2; ++i) { int R, C; stage_rc(tid * 16 + i * 8192, R, C); const int Rb = Epi::PERM ? ((R & ~31) + perm32(R & 31)) : R;
;         voffA[i] = (unsigned)(R * K + C) * 2u; voffB[i] = (unsigned)(Rb * K + C) * 2u; }
;     const size_t kstep = (size_t)(BK * 2);
;     const size_t hstep = (size_t)HALF * K * 2;
;     const size_t tstep = 2 * hstep;
;     const unsigned ldsw = (unsigned)wid * 1024u;
;     const int aoff = lds_byte(wr * 64 + fr, fq * 8), boff = lds_byte(wc * 32 + fr, fq * 8);
;     ...
;     Unit cur, nxt; int ui = 0;
;     if (!S.next(0, cur)) return;
;     f32x4 acc[2][2][4][2];
; #pragma unroll
;     for (int a = 0; a < 2; ++a)
; #pragma unroll
;         for (int b = 0; b < 2; ++b)
; #pragma unroll
;             for (int m = 0; m < 4; ++m)
; #pragma unroll
;                 for (int n = 0; n < 2; ++n) acc[a][b][m][n] = (f32x4){0.f, 0.f, 0.f, 0.f};
;     bf16x8 At[4][2], B0[2][2], B1[2][2];
;     const char* cA = (const char*)gA + (size_t)cur.pm * tstep; const char* cB = (const char*)gBt + (size_t)cur.pn * tstep;
;     PG8_STAGE(PG8_SB(0, 0), cB, voffB); PG8_STAGE(PG8_SB(0, 1), cB + hstep, voffB); PG8_STAGE(PG8_SA(0, 0), cA, voffA); PG8_STAGE(PG8_SA(0, 1), cA + hstep, voffA);
;     PG8_STAGE(PG8_SB(1, 0), cB + kstep, voffB); PG8_STAGE(PG8_SA(1, 0), cA + kstep, voffA); PG8_STAGE(PG8_SB(1, 1), cB + hstep + kstep, voffB);
.LBB0_656:
	s_mov_b32 s84, 0
	s_cmp_lg_u32 s64, 0x100
	s_cbranch_scc1 .Lp5a_k
	s_cmp_gt_u32 s86, 63
	s_cbranch_scc1 .Lp5a_k
	s_bfe_u32 s7, s86, 0x20003
	s_mul_i32 s84, s7, 0x600
	s_cmp_eq_u32 s7, 3
	s_cselect_b32 s7, 0x100, 0
	s_sub_i32 s84, s84, s7
.Lp5a_k:
	v_lshl_add_u32 v5, v0, 4, s33
	v_ashrrev_i32_e32 v1, 31, v5
	v_lshrrev_b32_e32 v1, 22, v1
	v_add_u32_e32 v1, v5, v1
	v_ashrrev_i32_e32 v1, 10, v1
	v_mul_i32_i24_e32 v2, 0x400, v1
	v_sub_u32_e32 v2, v5, v2
	v_lshrrev_b32_e32 v3, 4, v2
	v_bitop3_b32 v4, v3, v2, 32 bitop3:0x6c
	v_lshlrev_b32_e32 v2, 3, v1
	v_and_b32_e32 v3, -16, v2
	v_ashrrev_i32_e32 v2, 31, v4
	v_lshrrev_b32_e32 v2, 26, v2
	v_add_u32_e32 v6, v4, v2
	v_ashrrev_i32_e32 v2, 6, v6
	v_and_b32_e32 v6, 0xc0, v6
	v_add_u32_e32 v7, v2, v3
	v_sub_u32_e32 v4, v4, v6
	v_mov_b32_e32 v8, 1
	v_lshlrev_b32_e32 v3, 5, v1
	v_ashrrev_i16_sdwa v4, v8, sext(v4) dst_sel:DWORD dst_unused:UNUSED_PAD src0_sel:DWORD src1_sel:BYTE_0
	v_lshlrev_b32_e32 v9, 1, v7
	v_lshrrev_b32_e32 v10, 2, v7
	v_and_b32_e32 v11, 3, v2
	s_mov_b32 s6, 0xffffe0
	v_and_b32_e32 v3, 32, v3
	v_bfe_i32 v4, v4, 0, 16
	v_and_b32_e32 v9, 24, v9
	v_and_b32_e32 v10, 4, v10
	v_and_or_b32 v11, v7, s6, v11
	s_movk_i32 s16, 0xb00
	v_add_u32_e32 v6, v3, v4
	v_or3_b32 v9, v11, v10, v9
	v_mul_lo_u32 v7, v7, s16
	v_add_lshl_u32 v128, v6, v7, 1
	v_mul_u32_u24_e32 v7, 0xb00, v9
	v_add_lshl_u32 v130, v7, v6, 1
	v_add_u32_e32 v6, 0x2000, v5
	v_ashrrev_i32_e32 v5, 31, v6
	v_lshrrev_b32_e32 v5, 22, v5
	v_add_u32_e32 v5, v6, v5
	v_ashrrev_i32_e32 v5, 10, v5
	v_mul_i32_i24_e32 v7, 0x400, v5
	v_sub_u32_e32 v6, v6, v7
	v_lshrrev_b32_e32 v7, 4, v6
	v_bitop3_b32 v9, v7, v6, 32 bitop3:0x6c
	v_ashrrev_i32_e32 v7, 31, v9
	v_lshrrev_b32_e32 v7, 26, v7
	v_add_u32_e32 v10, v9, v7
	v_ashrrev_i32_e32 v7, 6, v10
	v_and_b32_e32 v10, 0xffc0, v10
	v_lshlrev_b32_e32 v6, 3, v5
	v_sub_u32_e32 v9, v9, v10
	s_add_u32 s2, s44, 0x1380000
	v_and_b32_e32 v6, -16, v6
	v_lshrrev_b16_e32 v10, 7, v9
	s_addc_u32 s3, s45, 0
	v_add_u32_e32 v11, v7, v6
	v_and_b32_e32 v10, 1, v10
	v_and_b32_e32 v13, 3, v7
	s_mul_i32 s7, s67, 0x160000
	v_add_u16_e32 v9, v9, v10
	v_lshlrev_b32_e32 v10, 1, v11
	v_lshrrev_b32_e32 v12, 2, v11
	v_and_or_b32 v13, v11, s6, v13
	s_mul_hi_i32 s6, s67, 0x160000
	s_add_u32 s42, s2, s7
	v_lshlrev_b32_e32 v6, 5, v5
	v_ashrrev_i16_sdwa v8, v8, sext(v9) dst_sel:DWORD dst_unused:UNUSED_PAD src0_sel:DWORD src1_sel:BYTE_0
	v_and_b32_e32 v10, 24, v10
	v_and_b32_e32 v12, 4, v12
	s_addc_u32 s43, s3, s6
	s_add_u32 s42, s42, s84
	s_addc_u32 s43, s43, 0
	s_add_i32 s29, s33, 0
	v_and_b32_e32 v6, 32, v6
	v_bfe_i32 v8, v8, 0, 16
	v_or3_b32 v10, v13, v12, v10
	s_add_i32 m0, s29, 0x10000
	v_add_u32_e32 v9, v6, v8
	v_mul_u32_u24_e32 v10, 0xb00, v10
	global_load_lds_dwordx4 v130, s[42:43]
	s_add_i32 m0, s29, 0x12000
	v_add_lshl_u32 v134, v10, v9, 1
	s_add_u32 s6, s42, 0xb0000
	global_load_lds_dwordx4 v134, s[42:43]
	s_addc_u32 s7, s43, 0
	s_add_i32 m0, s29, 0x14000
	s_mul_i32 s11, s68, 0x160000
	global_load_lds_dwordx4 v130, s[6:7]
	s_add_i32 m0, s29, 0x16000
	s_mul_hi_i32 s10, s68, 0x160000
	s_add_u32 s30, s80, s11
	s_addc_u32 s31, s81, s10
	s_add_u32 s30, s30, s84
	s_addc_u32 s31, s31, 0
	s_add_i32 s36, s29, 0x2000
	v_mul_lo_u32 v11, v11, s16
	global_load_lds_dwordx4 v134, s[6:7]
	s_mov_b32 m0, s29
	s_add_u32 s6, s30, 0xb0000
	v_add_lshl_u32 v132, v9, v11, 1
	global_load_lds_dwordx4 v128, s[30:31]
	s_mov_b32 m0, s36
	s_addc_u32 s7, s31, 0
	s_add_i32 s37, s29, 0x4000
	v_mov_b32_e32 v131, 0
	global_load_lds_dwordx4 v132, s[30:31]
	s_mov_b32 m0, s37
	s_add_i32 s38, s29, 0x6000
	v_lshl_add_u64 v[10:11], s[42:43], 0, v[130:131]
	v_mov_b32_e32 v135, v131
	global_load_lds_dwordx4 v128, s[6:7]
	s_mov_b32 m0, s38
	s_mov_b64 s[10:11], 0x80
	v_lshl_add_u64 v[12:13], s[42:43], 0, v[134:135]
	v_mov_b32_e32 v129, v131
	global_load_lds_dwordx4 v132, s[6:7]
	s_add_i32 m0, s29, 0x18000
	v_lshl_add_u64 v[10:11], v[10:11], 0, s[10:11]
	v_lshl_add_u64 v[14:15], s[30:31], 0, v[128:129]
	v_mov_b32_e32 v133, v131
	global_load_lds_dwordx4 v[10:11], off
	v_lshl_add_u64 v[10:11], v[12:13], 0, s[10:11]
	s_add_i32 m0, s29, 0x1a000
	s_add_i32 s39, s29, 0x8000
	v_lshl_add_u64 v[16:17], s[30:31], 0, v[132:133]
	global_load_lds_dwordx4 v[10:11], off
	v_lshl_add_u64 v[10:11], v[14:15], 0, s[10:11]
	s_mov_b32 m0, s39
	s_add_i32 s40, s29, 0xa000
	global_load_lds_dwordx4 v[10:11], off
	v_lshl_add_u64 v[10:11], v[16:17], 0, s[10:11]
	s_mov_b32 m0, s40
	s_add_u32 s6, s42, 0xb0080
	global_load_lds_dwordx4 v[10:11], off
	s_addc_u32 s7, s43, 0
	s_add_i32 m0, s29, 0x1c000
	s_mov_b32 s41, 0
	global_load_lds_dwordx4 v130, s[6:7]
	s_add_i32 m0, s29, 0x1e000
	s_nop 0
	global_load_lds_dwordx4 v134, s[6:7]
	v_readlane_b32 s6, v249, 42
	s_cmp_eq_u32 s6, 1
	s_cselect_b64 s[12:13], -1, 0
	s_cmp_lg_u32 s6, 1
	s_mov_b64 s[6:7], 0xb0080
	s_cbranch_scc1 .LBB0_658
	s_barrier

;     __device__ __forceinline__ bool next(int i, Unit& u) const {
;         constexpr int NU = (33792 / BM) * NN;
;         const int L = i * G + ((NU - i * G < G) ? vp : v); if (L >= NU) return false;
;         constexpr int NM = 33792 / BM, NFULL = (NM / 8) * 8 * NN;
;         if (L < NFULL) { const int g = L / (8 * NN), idx = L % (8 * NN); u.pm = g * 8 + (idx & 7); u.pn = idx >> 3; }
;         else { constexpr int GS = NM % 8 ? NM % 8 : 8; const int idx = L - NFULL; u.pm = (NM / 8) * 8 + idx % GS; u.pn = idx / GS; }
.LBB0_661:
	s_add_i32 s41, s41, 1
	s_mul_i32 s6, s41, s64
	s_sub_i32 s7, 0x210, s6
	s_cmp_lt_i32 s7, s64
	s_cselect_b32 s18, s0, s1
	s_add_i32 s18, s18, s6
	s_cmp_lg_u32 s64, 0x100
	s_cbranch_scc1 .Lp5a_sch
	s_cmp_gt_u32 s86, 63
	s_cbranch_scc1 .Lp5a_nt
	s_add_i32 s7, s41, -1
	s_lshl_b32 s7, s7, 8
	s_add_i32 s18, s7, s1
	s_cmp_lt_u32 s41, 3
	s_cbranch_scc1 .Lp5a_sch
	s_movk_i32 s18, 0x210
	s_branch .Lp5a_sch
.Lp5a_nt:
	s_cmp_lt_u32 s41, 2
	s_cbranch_scc1 .Lp5a_sch
	s_movk_i32 s18, 0x210

; template <int KK, class Epi, class Sched, bool ALIGN_EPI = true>
; __device__ __forceinline__ void gemm_phase(LAS unsigned char* lds, const bf16* gA, const bf16* gBt, const Sched& S, const Epi& E, const int wid) {
;     ...
;         const char* nA = has_next ? (const char*)gA + (size_t)nxt.pm * tstep : cA; const char* nB = has_next ? (const char*)gBt + (size_t)nxt.pn * tstep : cB;
; #pragma unroll 1
;         for (int t = 0; t < nt; t += 2) {
;             const bool last = (t == nt - 2);
;             const char* a1 = cA + (size_t)(t + 1) * kstep;
;             const char* a2 = last ? nA : cA + (size_t)(t + 2) * kstep; const char* b2 = last ? nB : cB + (size_t)(t + 2) * kstep;
;             const char* a3 = a2 + kstep; const char* b3 = b2 + kstep;
.LBB0_670:
	s_add_u32 s69, s42, 0x100
	v_mov_b32_e32 v0, 0
	s_addc_u32 s70, s43, 0
	s_mov_b32 s71, -2
	s_cmp_lg_u32 s64, 0x100
	s_cbranch_scc1 .Lp5a_cnt
	s_cmp_lg_u32 s41, 1
	s_cbranch_scc1 .Lp5a_cnt
	s_cmp_gt_u32 s86, 63
	s_cbranch_scc1 .Lp5a_cnt
	s_bfe_u32 s82, s86, 0x10004
	s_lshl_b32 s82, s82, 1
	s_add_i32 s71, s82, 30

; #define PG8_BAR __builtin_amdgcn_s_barrier()
; template <int KK, class Epi, class Sched, bool ALIGN_EPI = true>
; __device__ __forceinline__ void gemm_phase(LAS unsigned char* lds, const bf16* gA, const bf16* gBt, const Sched& S, const Epi& E, const int wid) {
;     ...
;         if constexpr (ALIGN_EPI) { if (wr == 0) PG8_BAR; }
;         E(acc, cur, wr, wc, fr, fq);
;         if (!has_next) break;
.LBB0_674:
	s_cmp_lg_u32 s64, 0x100
	s_cbranch_scc1 .Lp5a_epi
	s_cmp_lg_u32 s41, 1
	s_cbranch_scc1 .Lp5a_epi
	s_cmp_gt_u32 s86, 63
	s_cbranch_scc1 .Lp5a_epi
	s_bfe_u32 s32, s86, 0x20003
	s_and_b32 s90, s86, 7
	s_lshl_b32 s90, s90, 1
	s_bfe_u32 s88, s86, 0x10005
	s_add_i32 s90, s90, s88
	v_readlane_b32 s88, v249, 0
	v_lshlrev_b32_e32 v140, 4, v196
	s_nop 1
	s_lshl_b32 s89, s88, 10
	v_add_u32_e32 v140, s89, v140
	s_mul_i32 s89, s90, 3
	s_lshl_b32 s89, s89, 18
	s_add_u32 s76, s46, s89
	s_addc_u32 s77, s47, 0
	s_add_u32 s76, s76, 0x0
	s_addc_u32 s77, s77, 0
	s_cmp_eq_u32 s32, 0
	s_cbranch_scc1 .Lp5a_cons
	s_add_i32 s89, s32, -1
	s_lshl_b32 s89, s89, 18
	s_add_u32 s76, s76, s89
	s_addc_u32 s77, s77, 0
	s_nop 7
	global_store_dwordx4 v140, v[0:3], s[76:77] sc0 sc1
	s_add_u32 s76, s76, 0x2000
	s_addc_u32 s77, s77, 0
	global_store_dwordx4 v140, v[4:7], s[76:77] sc0 sc1
	s_add_u32 s76, s76, 0x2000
	s_addc_u32 s77, s77, 0
	global_store_dwordx4 v140, v[8:11], s[76:77] sc0 sc1
	s_add_u32 s76, s76, 0x2000
	s_addc_u32 s77, s77, 0
	global_store_dwordx4 v140, v[12:15], s[76:77] sc0 sc1
	s_add_u32 s76, s76, 0x2000
	s_addc_u32 s77, s77, 0
	global_store_dwordx4 v140, v[16:19], s[76:77] sc0 sc1
	s_add_u32 s76, s76, 0x2000
	s_addc_u32 s77, s77, 0
	global_store_dwordx4 v140, v[20:23], s[76:77] sc0 sc1
	s_add_u32 s76, s76, 0x2000
	s_addc_u32 s77, s77, 0
	global_store_dwordx4 v140, v[24:27], s[76:77] sc0 sc1
	s_add_u32 s76, s76, 0x2000
	s_addc_u32 s77, s77, 0
	global_store_dwordx4 v140, v[28:31], s[76:77] sc0 sc1
	s_add_u32 s76, s76, 0x2000
	s_addc_u32 s77, s77, 0
	global_store_dwordx4 v140, v[32:35], s[76:77] sc0 sc1
	s_add_u32 s76, s76, 0x2000
	s_addc_u32 s77, s77, 0
	global_store_dwordx4 v140, v[36:39], s[76:77] sc0 sc1
	s_add_u32 s76, s76, 0x2000
	s_addc_u32 s77, s77, 0
	global_store_dwordx4 v140, v[40:43], s[76:77] sc0 sc1
	s_add_u32 s76, s76, 0x2000
	s_addc_u32 s77, s77, 0
	global_store_dwordx4 v140, v[44:47], s[76:77] sc0 sc1
	s_add_u32 s76, s76, 0x2000
	s_addc_u32 s77, s77, 0
	global_store_dwordx4 v140, v[48:51], s[76:77] sc0 sc1
	s_add_u32 s76, s76, 0x2000
	s_addc_u32 s77, s77, 0
	global_store_dwordx4 v140, v[52:55], s[76:77] sc0 sc1
	s_add_u32 s76, s76, 0x2000
	s_addc_u32 s77, s77, 0
	global_store_dwordx4 v140, v[56:59], s[76:77] sc0 sc1
	s_add_u32 s76, s76, 0x2000
	s_addc_u32 s77, s77, 0
	global_store_dwordx4 v140, v[60:63], s[76:77] sc0 sc1
	s_add_u32 s76, s76, 0x2000
	s_addc_u32 s77, s77, 0
	global_store_dwordx4 v140, v[64:67], s[76:77] sc0 sc1
	s_add_u32 s76, s76, 0x2000
	s_addc_u32 s77, s77, 0
	global_store_dwordx4 v140, v[68:71], s[76:77] sc0 sc1
	s_add_u32 s76, s76, 0x2000
	s_addc_u32 s77, s77, 0
	global_store_dwordx4 v140, v[72:75], s[76:77] sc0 sc1
	s_add_u32 s76, s76, 0x2000
	s_addc_u32 s77, s77, 0
	global_store_dwordx4 v140, v[76:79], s[76:77] sc0 sc1
	s_add_u32 s76, s76, 0x2000
	s_addc_u32 s77, s77, 0
	global_store_dwordx4 v140, v[80:83], s[76:77] sc0 sc1
	s_add_u32 s76, s76, 0x2000
	s_addc_u32 s77, s77, 0
	global_store_dwordx4 v140, v[84:87], s[76:77] sc0 sc1
	s_add_u32 s76, s76, 0x2000
	s_addc_u32 s77, s77, 0
	global_store_dwordx4 v140, v[88:91], s[76:77] sc0 sc1
	s_add_u32 s76, s76, 0x2000
	s_addc_u32 s77, s77, 0
	global_store_dwordx4 v140, v[92:95], s[76:77] sc0 sc1
	s_add_u32 s76, s76, 0x2000
	s_addc_u32 s77, s77, 0
	global_store_dwordx4 v140, v[96:99], s[76:77] sc0 sc1
	s_add_u32 s76, s76, 0x2000
	s_addc_u32 s77, s77, 0
	global_store_dwordx4 v140, v[100:103], s[76:77] sc0 sc1
	s_add_u32 s76, s76, 0x2000
	s_addc_u32 s77, s77, 0
	global_store_dwordx4 v140, v[104:107], s[76:77] sc0 sc1
	s_add_u32 s76, s76, 0x2000
	s_addc_u32 s77, s77, 0
	global_store_dwordx4 v140, v[108:111], s[76:77] sc0 sc1
	s_add_u32 s76, s76, 0x2000
	s_addc_u32 s77, s77, 0
	global_store_dwordx4 v140, v[112:115], s[76:77] sc0 sc1
	s_add_u32 s76, s76, 0x2000
	s_addc_u32 s77, s77, 0
	global_store_dwordx4 v140, v[116:119], s[76:77] sc0 sc1
	s_add_u32 s76, s76, 0x2000
	s_addc_u32 s77, s77, 0
	global_store_dwordx4 v140, v[120:123], s[76:77] sc0 sc1
	s_add_u32 s76, s76, 0x2000
	s_addc_u32 s77, s77, 0
	global_store_dwordx4 v140, v[124:127], s[76:77] sc0 sc1
	s_waitcnt vmcnt(0)
	s_lshl_b32 s89, s90, 2
	s_add_i32 s89, s89, s32
	s_lshl_b32 s89, s89, 2
	v_mov_b32_e32 v141, s89
	v_mov_b32_e32 v142, 1
	s_mov_b64 s[78:79], exec
	s_mov_b64 exec, 1
	global_atomic_add v141, v142, s[44:45] offset:3200
	s_mov_b64 exec, s[78:79]
	s_and_b64 vcc, exec, s[6:7]
	s_mov_b64 s[30:31], -1
	s_branch .Lp5a_skip

; #define PG8_BAR __builtin_amdgcn_s_barrier()
; template <int KK, class Epi, class Sched, bool ALIGN_EPI = true>
; __device__ __forceinline__ void gemm_phase(LAS unsigned char* lds, const bf16* gA, const bf16* gBt, const Sched& S, const Epi& E, const int wid) {
;     ...
;         cur = nxt; cA = nA; cB = nB; ++ui;
;         if constexpr (ALIGN_EPI) { if (wr == 1) PG8_BAR; }
;     }
.Lp5a_skip:
	s_cbranch_vccnz .LBB0_660
	s_andn2_b64 vcc, exec, s[12:13]
	s_cbranch_vccnz .LBB0_659
	s_barrier
	s_branch .LBB0_659

;     __device__ __forceinline__ bool next(int i, Unit& u) const {
;         constexpr int NU = (33792 / BM) * NN;
;         const int L = i * G + ((NU - i * G < G) ? vp : v); if (L >= NU) return false;
;         constexpr int NM = 33792 / BM, NFULL = (NM / 8) * 8 * NN;
;         if (L < NFULL) { const int g = L / (8 * NN), idx = L % (8 * NN); u.pm = g * 8 + (idx & 7); u.pn = idx >> 3; }
;         else { constexpr int GS = NM % 8 ? NM % 8 : 8; const int idx = L - NFULL; u.pm = (NM / 8) * 8 + idx % GS; u.pn = idx / GS; }
.LBB0_1272:
	v_readlane_b32 s2, v249, 17
	v_readlane_b32 s3, v249, 18
	s_and_b64 s[2:3], s[2:3], exec
	s_cselect_b32 s2, s1, s0
	s_cmp_lg_u32 s64, 0x100
	s_cbranch_scc1 .Lp5b_f
	s_cmp_gt_u32 s86, 63
	s_cbranch_scc1 .Lp5b_f
	s_and_b32 s7, s86, 7
	s_lshl_b32 s7, s7, 1
	s_bfe_u32 s2, s86, 0x10005
	s_add_i32 s2, s2, s7
	s_addk_i32 s2, 0x200
.Lp5b_f:
	v_mov_b32_e32 v0, v196
	s_cmpk_gt_i32 s2, 0x20f
	s_cbranch_scc1 .LBB0_1301
	s_cmpk_gt_i32 s2, 0x1ff
	s_cbranch_scc0 .LBB0_1277
	s_add_i32 s3, s2, 0xfffffe00
	s_and_b32 s6, s2, 3
	s_or_b32 s58, s6, 0x80
	s_lshr_b32 s57, s3, 2
	s_cbranch_execz .LBB0_1278
	s_branch .LBB0_1279

; #define PG8_STAGE(bufoff, gbase, voff) do { _Pragma("unroll") for (int _i = 0; _i < 2; ++_i) \
;         __builtin_amdgcn_global_load_lds((const unsigned*)((const char*)(gbase) + (voff)[_i]), (LAS unsigned*)(lds + (bufoff) + ldsw + _i * 8192), 16, 0, 0); } while (0)
; template <int KK, class Epi, class Sched, bool ALIGN_EPI = true>
; __device__ __forceinline__ void gemm_phase(LAS unsigned char* lds, const bf16* gA, const bf16* gBt, const Sched& S, const Epi& E, const int wid) {
;     ...
;     unsigned voffA[2], voffB[2];
; #pragma unroll
;     for (int i = 0; i < 2; ++i) { int R, C; stage_rc(tid * 16 + i * 8192, R, C); const int Rb = Epi::PERM ? ((R & ~31) + perm32(R & 31)) : R;
;         voffA[i] = (unsigned)(R * K + C) * 2u; voffB[i] = (unsigned)(Rb * K + C) * 2u; }
;     const size_t kstep = (size_t)(BK * 2);
;     const size_t hstep = (size_t)HALF * K * 2;
;     const size_t tstep = 2 * hstep;
;     const unsigned ldsw = (unsigned)wid * 1024u;
;     const int aoff = lds_byte(wr * 64 + fr, fq * 8), boff = lds_byte(wc * 32 + fr, fq * 8);
;     ...
;     Unit cur, nxt; int ui = 0;
;     if (!S.next(0, cur)) return;
;     f32x4 acc[2][2][4][2];
; #pragma unroll
;     for (int a = 0; a < 2; ++a)
; #pragma unroll
;         for (int b = 0; b < 2; ++b)
; #pragma unroll
;             for (int m = 0; m < 4; ++m)
; #pragma unroll
;                 for (int n = 0; n < 2; ++n) acc[a][b][m][n] = (f32x4){0.f, 0.f, 0.f, 0.f};
;     bf16x8 At[4][2], B0[2][2], B1[2][2];
;     const char* cA = (const char*)gA + (size_t)cur.pm * tstep; const char* cB = (const char*)gBt + (size_t)cur.pn * tstep;
;     PG8_STAGE(PG8_SB(0, 0), cB, voffB); PG8_STAGE(PG8_SB(0, 1), cB + hstep, voffB); PG8_STAGE(PG8_SA(0, 0), cA, voffA); PG8_STAGE(PG8_SA(0, 1), cA + hstep, voffA);
;     PG8_STAGE(PG8_SB(1, 0), cB + kstep, voffB); PG8_STAGE(PG8_SA(1, 0), cA + kstep, voffA); PG8_STAGE(PG8_SB(1, 1), cB + hstep + kstep, voffB);
.LBB0_1279:
	s_mov_b32 s66, 0
	s_cmp_lg_u32 s64, 0x100
	s_cbranch_scc1 .Lp5b_k
	s_cmp_gt_u32 s86, 63
	s_cbranch_scc1 .Lp5b_k
	s_bfe_u32 s7, s86, 0x20003
	s_mul_i32 s66, s7, 0x600
	s_cmp_eq_u32 s7, 3
	s_cselect_b32 s7, 0x100, 0
	s_sub_i32 s66, s66, s7
.Lp5b_k:
	v_lshl_add_u32 v5, v0, 4, s33
	v_ashrrev_i32_e32 v1, 31, v5
	v_lshrrev_b32_e32 v1, 22, v1
	v_add_u32_e32 v1, v5, v1
	v_ashrrev_i32_e32 v1, 10, v1
	v_mul_i32_i24_e32 v2, 0x400, v1
	v_sub_u32_e32 v2, v5, v2
	v_lshrrev_b32_e32 v3, 4, v2
	v_bitop3_b32 v4, v3, v2, 32 bitop3:0x6c
	v_lshlrev_b32_e32 v2, 3, v1
	v_and_b32_e32 v3, -16, v2
	v_ashrrev_i32_e32 v2, 31, v4
	v_lshrrev_b32_e32 v2, 26, v2
	v_add_u32_e32 v6, v4, v2
	v_ashrrev_i32_e32 v2, 6, v6
	v_and_b32_e32 v6, 0xc0, v6
	v_add_u32_e32 v7, v2, v3
	v_sub_u32_e32 v4, v4, v6
	v_mov_b32_e32 v8, 1
	v_lshlrev_b32_e32 v3, 5, v1
	v_ashrrev_i16_sdwa v4, v8, sext(v4) dst_sel:DWORD dst_unused:UNUSED_PAD src0_sel:DWORD src1_sel:BYTE_0
	v_lshlrev_b32_e32 v9, 1, v7
	v_lshrrev_b32_e32 v10, 2, v7
	v_and_b32_e32 v11, 3, v2
	s_mov_b32 s6, 0xffffe0
	v_and_b32_e32 v3, 32, v3
	v_bfe_i32 v4, v4, 0, 16
	v_and_b32_e32 v9, 24, v9
	v_and_b32_e32 v10, 4, v10
	v_and_or_b32 v11, v7, s6, v11
	s_movk_i32 s14, 0xb00
	v_add_u32_e32 v6, v3, v4
	v_or3_b32 v9, v11, v10, v9
	v_mul_lo_u32 v7, v7, s14
	v_add_lshl_u32 v128, v6, v7, 1
	v_mul_u32_u24_e32 v7, 0xb00, v9
	v_add_lshl_u32 v130, v7, v6, 1
	v_add_u32_e32 v6, 0x2000, v5
	v_ashrrev_i32_e32 v5, 31, v6
	v_lshrrev_b32_e32 v5, 22, v5
	v_add_u32_e32 v5, v6, v5
	v_ashrrev_i32_e32 v5, 10, v5
	v_mul_i32_i24_e32 v7, 0x400, v5
	v_sub_u32_e32 v6, v6, v7
	v_lshrrev_b32_e32 v7, 4, v6
	v_bitop3_b32 v9, v7, v6, 32 bitop3:0x6c
	v_ashrrev_i32_e32 v7, 31, v9
	v_lshrrev_b32_e32 v7, 26, v7
	v_add_u32_e32 v10, v9, v7
	v_ashrrev_i32_e32 v7, 6, v10
	v_and_b32_e32 v10, 0xffc0, v10
	v_lshlrev_b32_e32 v6, 3, v5
	v_sub_u32_e32 v9, v9, v10
	s_add_u32 s2, s20, 0x2d00000
	v_and_b32_e32 v6, -16, v6
	v_lshrrev_b16_e32 v10, 7, v9
	s_addc_u32 s3, s21, 0
	v_add_u32_e32 v11, v7, v6
	v_and_b32_e32 v10, 1, v10
	v_and_b32_e32 v13, 3, v7
	s_mul_i32 s7, s57, 0x160000
	v_add_u16_e32 v9, v9, v10
	v_lshlrev_b32_e32 v10, 1, v11
	v_lshrrev_b32_e32 v12, 2, v11
	v_and_or_b32 v13, v11, s6, v13
	s_mul_hi_i32 s6, s57, 0x160000
	s_add_u32 s26, s2, s7
	v_lshlrev_b32_e32 v6, 5, v5
	v_ashrrev_i16_sdwa v8, v8, sext(v9) dst_sel:DWORD dst_unused:UNUSED_PAD src0_sel:DWORD src1_sel:BYTE_0
	v_and_b32_e32 v10, 24, v10
	v_and_b32_e32 v12, 4, v12
	s_addc_u32 s27, s3, s6
	s_add_u32 s26, s26, s66
	s_addc_u32 s27, s27, 0
	s_add_i32 s18, s33, 0
	v_and_b32_e32 v6, 32, v6
	v_bfe_i32 v8, v8, 0, 16
	v_or3_b32 v10, v13, v12, v10
	s_add_i32 m0, s18, 0x10000
	v_add_u32_e32 v9, v6, v8
	v_mul_u32_u24_e32 v10, 0xb00, v10
	global_load_lds_dwordx4 v130, s[26:27]
	s_add_i32 m0, s18, 0x12000
	v_add_lshl_u32 v134, v10, v9, 1
	s_add_u32 s6, s26, 0xb0000
	global_load_lds_dwordx4 v134, s[26:27]
	s_addc_u32 s7, s27, 0
	s_add_i32 m0, s18, 0x14000
	s_mul_i32 s9, s58, 0x160000
	global_load_lds_dwordx4 v130, s[6:7]
	s_add_i32 m0, s18, 0x16000
	s_mul_hi_i32 s8, s58, 0x160000
	s_add_u32 s24, s5, s9
	s_addc_u32 s25, s29, s8
	s_add_u32 s24, s24, s66
	s_addc_u32 s25, s25, 0
	s_add_i32 s19, s18, 0x2000
	v_mul_lo_u32 v11, v11, s14
	global_load_lds_dwordx4 v134, s[6:7]
	s_mov_b32 m0, s18
	s_add_u32 s6, s24, 0xb0000
	v_add_lshl_u32 v132, v9, v11, 1
	global_load_lds_dwordx4 v128, s[24:25]
	s_mov_b32 m0, s19
	s_addc_u32 s7, s25, 0
	s_add_i32 s38, s18, 0x4000
	v_mov_b32_e32 v131, 0
	global_load_lds_dwordx4 v132, s[24:25]
	s_mov_b32 m0, s38
	s_add_i32 s39, s18, 0x6000
	v_lshl_add_u64 v[10:11], s[26:27], 0, v[130:131]
	v_mov_b32_e32 v135, v131
	global_load_lds_dwordx4 v128, s[6:7]
	s_mov_b32 m0, s39
	s_mov_b64 s[8:9], 0x80
	v_lshl_add_u64 v[12:13], s[26:27], 0, v[134:135]
	v_mov_b32_e32 v129, v131
	global_load_lds_dwordx4 v132, s[6:7]
	s_add_i32 m0, s18, 0x18000
	v_lshl_add_u64 v[10:11], v[10:11], 0, s[8:9]
	v_lshl_add_u64 v[14:15], s[24:25], 0, v[128:129]
	v_mov_b32_e32 v133, v131
	global_load_lds_dwordx4 v[10:11], off
	v_lshl_add_u64 v[10:11], v[12:13], 0, s[8:9]
	s_add_i32 m0, s18, 0x1a000
	s_add_i32 s40, s18, 0x8000
	v_lshl_add_u64 v[16:17], s[24:25], 0, v[132:133]
	global_load_lds_dwordx4 v[10:11], off
	v_lshl_add_u64 v[10:11], v[14:15], 0, s[8:9]
	s_mov_b32 m0, s40
	s_add_i32 s41, s18, 0xa000
	global_load_lds_dwordx4 v[10:11], off
	v_lshl_add_u64 v[10:11], v[16:17], 0, s[8:9]
	s_mov_b32 m0, s41
	s_add_u32 s6, s26, 0xb0080
	global_load_lds_dwordx4 v[10:11], off
	s_addc_u32 s7, s27, 0
	s_add_i32 m0, s18, 0x1c000
	s_mov_b32 s42, 0
	global_load_lds_dwordx4 v130, s[6:7]
	s_add_i32 m0, s18, 0x1e000
	s_nop 0
	global_load_lds_dwordx4 v134, s[6:7]
	v_readlane_b32 s6, v249, 42
	s_cmp_eq_u32 s6, 1
	s_cselect_b64 s[10:11], -1, 0
	s_cmp_lg_u32 s6, 1
	s_mov_b64 s[6:7], 0xb0080
	s_cbranch_scc1 .LBB0_1281
	s_barrier

;     __device__ __forceinline__ bool next(int i, Unit& u) const {
;         constexpr int NU = (33792 / BM) * NN;
;         const int L = i * G + ((NU - i * G < G) ? vp : v); if (L >= NU) return false;
;         constexpr int NM = 33792 / BM, NFULL = (NM / 8) * 8 * NN;
;         if (L < NFULL) { const int g = L / (8 * NN), idx = L % (8 * NN); u.pm = g * 8 + (idx & 7); u.pn = idx >> 3; }
;         else { constexpr int GS = NM % 8 ? NM % 8 : 8; const int idx = L - NFULL; u.pm = (NM / 8) * 8 + idx % GS; u.pn = idx / GS; }
.LBB0_1284:
	s_add_i32 s42, s42, 1
	s_mul_i32 s6, s42, s64
	s_sub_i32 s7, 0x210, s6
	s_cmp_lt_i32 s7, s64
	s_cselect_b32 s16, s1, s0
	s_add_i32 s16, s16, s6
	s_cmp_lg_u32 s64, 0x100
	s_cbranch_scc1 .Lp5b_sch
	s_cmp_gt_u32 s86, 63
	s_cbranch_scc1 .Lp5b_nt
	s_add_i32 s7, s42, -1
	s_lshl_b32 s7, s7, 8
	s_add_i32 s16, s7, s0
	s_cmp_lt_u32 s42, 3
	s_cbranch_scc1 .Lp5b_sch
	s_movk_i32 s16, 0x210
	s_branch .Lp5b_sch
.Lp5b_nt:
	s_cmp_lt_u32 s42, 2
	s_cbranch_scc1 .Lp5b_sch
	s_movk_i32 s16, 0x210

; template <int KK, class Epi, class Sched, bool ALIGN_EPI = true>
; __device__ __forceinline__ void gemm_phase(LAS unsigned char* lds, const bf16* gA, const bf16* gBt, const Sched& S, const Epi& E, const int wid) {
;     ...
;         const char* nA = has_next ? (const char*)gA + (size_t)nxt.pm * tstep : cA; const char* nB = has_next ? (const char*)gBt + (size_t)nxt.pn * tstep : cB;
; #pragma unroll 1
;         for (int t = 0; t < nt; t += 2) {
;             const bool last = (t == nt - 2);
;             const char* a1 = cA + (size_t)(t + 1) * kstep;
;             const char* a2 = last ? nA : cA + (size_t)(t + 2) * kstep; const char* b2 = last ? nB : cB + (size_t)(t + 2) * kstep;
;             const char* a3 = a2 + kstep; const char* b3 = b2 + kstep;
.LBB0_1293:
	s_add_u32 s59, s26, 0x100
	v_mov_b32_e32 v0, 0
	s_addc_u32 s60, s27, 0
	s_mov_b32 s61, -2
	s_cmp_lg_u32 s64, 0x100
	s_cbranch_scc1 .Lp5b_cnt
	s_cmp_lg_u32 s42, 1
	s_cbranch_scc1 .Lp5b_cnt
	s_cmp_gt_u32 s86, 63
	s_cbranch_scc1 .Lp5b_cnt
	s_bfe_u32 s65, s86, 0x10004
	s_lshl_b32 s65, s65, 1
	s_add_i32 s61, s65, 30

; #define PG8_BAR __builtin_amdgcn_s_barrier()
; template <int KK, class Epi, class Sched, bool ALIGN_EPI = true>
; __device__ __forceinline__ void gemm_phase(LAS unsigned char* lds, const bf16* gA, const bf16* gBt, const Sched& S, const Epi& E, const int wid) {
;     ...
;         if constexpr (ALIGN_EPI) { if (wr == 0) PG8_BAR; }
;         E(acc, cur, wr, wc, fr, fq);
;         if (!has_next) break;
; #pragma unroll
;         for (int a = 0; a < 2; ++a)
; #pragma unroll
;             for (int b = 0; b < 2; ++b)
; #pragma unroll
;                 for (int m = 0; m < 4; ++m)
; #pragma unroll
;                     for (int n = 0; n < 2; ++n) acc[a][b][m][n] = (f32x4){0.f, 0.f, 0.f, 0.f};
;         cur = nxt; cA = nA; cB = nB; ++ui;
;         if constexpr (ALIGN_EPI) { if (wr == 1) PG8_BAR; }
;     }
.LBB0_1297:
	s_cmp_lg_u32 s64, 0x100
	s_cbranch_scc1 .Lp5b_epi
	s_cmp_lg_u32 s42, 1
	s_cbranch_scc1 .Lp5b_epi
	s_cmp_gt_u32 s86, 63
	s_cbranch_scc1 .Lp5b_epi
	s_bfe_u32 s65, s86, 0x20003
	s_and_b32 s67, s86, 7
	s_lshl_b32 s67, s67, 1
	s_bfe_u32 s68, s86, 0x10005
	s_add_i32 s67, s67, s68
	v_readlane_b32 s68, v249, 0
	v_lshlrev_b32_e32 v140, 4, v196
	s_nop 1
	s_lshl_b32 s69, s68, 10
	v_add_u32_e32 v140, s69, v140
	s_mul_i32 s69, s67, 3
	s_lshl_b32 s69, s69, 18
	s_add_u32 s70, s22, s69
	s_addc_u32 s71, s23, 0
	s_add_u32 s70, s70, 0xc00000
	s_addc_u32 s71, s71, 0
	s_cmp_eq_u32 s65, 0
	s_cbranch_scc1 .Lp5b_cons
	s_add_i32 s69, s65, -1
	s_lshl_b32 s69, s69, 18
	s_add_u32 s70, s70, s69
	s_addc_u32 s71, s71, 0
	s_nop 7
	global_store_dwordx4 v140, v[0:3], s[70:71] sc0 sc1
	s_add_u32 s70, s70, 0x2000
	s_addc_u32 s71, s71, 0
	global_store_dwordx4 v140, v[4:7], s[70:71] sc0 sc1
	s_add_u32 s70, s70, 0x2000
	s_addc_u32 s71, s71, 0
	global_store_dwordx4 v140, v[8:11], s[70:71] sc0 sc1
	s_add_u32 s70, s70, 0x2000
	s_addc_u32 s71, s71, 0
	global_store_dwordx4 v140, v[12:15], s[70:71] sc0 sc1
	s_add_u32 s70, s70, 0x2000
	s_addc_u32 s71, s71, 0
	global_store_dwordx4 v140, v[16:19], s[70:71] sc0 sc1
	s_add_u32 s70, s70, 0x2000
	s_addc_u32 s71, s71, 0
	global_store_dwordx4 v140, v[20:23], s[70:71] sc0 sc1
	s_add_u32 s70, s70, 0x2000
	s_addc_u32 s71, s71, 0
	global_store_dwordx4 v140, v[24:27], s[70:71] sc0 sc1
	s_add_u32 s70, s70, 0x2000
	s_addc_u32 s71, s71, 0
	global_store_dwordx4 v140, v[28:31], s[70:71] sc0 sc1
	s_add_u32 s70, s70, 0x2000
	s_addc_u32 s71, s71, 0
	global_store_dwordx4 v140, v[32:35], s[70:71] sc0 sc1
	s_add_u32 s70, s70, 0x2000
	s_addc_u32 s71, s71, 0
	global_store_dwordx4 v140, v[36:39], s[70:71] sc0 sc1
	s_add_u32 s70, s70, 0x2000
	s_addc_u32 s71, s71, 0
	global_store_dwordx4 v140, v[40:43], s[70:71] sc0 sc1
	s_add_u32 s70, s70, 0x2000
	s_addc_u32 s71, s71, 0
	global_store_dwordx4 v140, v[44:47], s[70:71] sc0 sc1
	s_add_u32 s70, s70, 0x2000
	s_addc_u32 s71, s71, 0
	global_store_dwordx4 v140, v[48:51], s[70:71] sc0 sc1
	s_add_u32 s70, s70, 0x2000
	s_addc_u32 s71, s71, 0
	global_store_dwordx4 v140, v[52:55], s[70:71] sc0 sc1
	s_add_u32 s70, s70, 0x2000
	s_addc_u32 s71, s71, 0
	global_store_dwordx4 v140, v[56:59], s[70:71] sc0 sc1
	s_add_u32 s70, s70, 0x2000
	s_addc_u32 s71, s71, 0
	global_store_dwordx4 v140, v[60:63], s[70:71] sc0 sc1
	s_add_u32 s70, s70, 0x2000
	s_addc_u32 s71, s71, 0
	global_store_dwordx4 v140, v[64:67], s[70:71] sc0 sc1
	s_add_u32 s70, s70, 0x2000
	s_addc_u32 s71, s71, 0
	global_store_dwordx4 v140, v[68:71], s[70:71] sc0 sc1
	s_add_u32 s70, s70, 0x2000
	s_addc_u32 s71, s71, 0
	global_store_dwordx4 v140, v[72:75], s[70:71] sc0 sc1
	s_add_u32 s70, s70, 0x2000
	s_addc_u32 s71, s71, 0
	global_store_dwordx4 v140, v[76:79], s[70:71] sc0 sc1
	s_add_u32 s70, s70, 0x2000
	s_addc_u32 s71, s71, 0
	global_store_dwordx4 v140, v[80:83], s[70:71] sc0 sc1
	s_add_u32 s70, s70, 0x2000
	s_addc_u32 s71, s71, 0
	global_store_dwordx4 v140, v[84:87], s[70:71] sc0 sc1
	s_add_u32 s70, s70, 0x2000
	s_addc_u32 s71, s71, 0
	global_store_dwordx4 v140, v[88:91], s[70:71] sc0 sc1
	s_add_u32 s70, s70, 0x2000
	s_addc_u32 s71, s71, 0
	global_store_dwordx4 v140, v[92:95], s[70:71] sc0 sc1
	s_add_u32 s70, s70, 0x2000
	s_addc_u32 s71, s71, 0
	global_store_dwordx4 v140, v[96:99], s[70:71] sc0 sc1
	s_add_u32 s70, s70, 0x2000
	s_addc_u32 s71, s71, 0
	global_store_dwordx4 v140, v[100:103], s[70:71] sc0 sc1
	s_add_u32 s70, s70, 0x2000
	s_addc_u32 s71, s71, 0
	global_store_dwordx4 v140, v[104:107], s[70:71] sc0 sc1
	s_add_u32 s70, s70, 0x2000
	s_addc_u32 s71, s71, 0
	global_store_dwordx4 v140, v[108:111], s[70:71] sc0 sc1
	s_add_u32 s70, s70, 0x2000
	s_addc_u32 s71, s71, 0
	global_store_dwordx4 v140, v[112:115], s[70:71] sc0 sc1
	s_add_u32 s70, s70, 0x2000
	s_addc_u32 s71, s71, 0
	global_store_dwordx4 v140, v[116:119], s[70:71] sc0 sc1
	s_add_u32 s70, s70, 0x2000
	s_addc_u32 s71, s71, 0
	global_store_dwordx4 v140, v[120:123], s[70:71] sc0 sc1
	s_add_u32 s70, s70, 0x2000
	s_addc_u32 s71, s71, 0
	global_store_dwordx4 v140, v[124:127], s[70:71] sc0 sc1
	s_waitcnt vmcnt(0)
	s_lshl_b32 s69, s67, 2
	s_add_i32 s69, s69, s65
	s_lshl_b32 s69, s69, 2
	v_mov_b32_e32 v141, s69
	v_mov_b32_e32 v142, 1
	s_mov_b64 s[72:73], exec
	s_mov_b64 exec, 1
	global_atomic_add v141, v142, s[20:21] offset:3200
	s_mov_b64 exec, s[72:73]
	s_and_b64 vcc, exec, s[6:7]
	s_mov_b64 s[6:7], -1
	s_branch .Lp5b_skip
.Lp5b_cons:
	s_lshl_b32 s69, s67, 4
	v_mov_b32_e32 v141, s69
.Lp5b_poll2:
	global_load_dword v142, v141, s[20:21] offset:3208 sc1
	s_waitcnt vmcnt(0)
	v_readfirstlane_b32 s32, v142
	s_nop 0
	s_cmp_ge_u32 s32, 16
	s_cbranch_scc1 .Lp5b_go2
	s_sleep 1
	s_branch .Lp5b_poll2
.Lp5b_go2:
.Lp5b_poll3:
	global_load_dword v142, v141, s[20:21] offset:3212 sc1
	s_waitcnt vmcnt(0)
	v_readfirstlane_b32 s32, v142
	s_nop 0
	s_cmp_ge_u32 s32, 16
	s_cbranch_scc1 .Lp5b_go3
	s_sleep 1
	s_branch .Lp5b_poll3
.Lp5b_go3:
.Lp5b_poll1:
	global_load_dword v142, v141, s[20:21] offset:3204 sc1
	s_waitcnt vmcnt(0)
	v_readfirstlane_b32 s32, v142
	s_nop 0
	s_cmp_ge_u32 s32, 16
	s_cbranch_scc1 .Lp5b_go1
	s_sleep 1
	s_branch .Lp5b_poll1

; #define PG8_BAR __builtin_amdgcn_s_barrier()
; template <int KK, class Epi, class Sched, bool ALIGN_EPI = true>
; __device__ __forceinline__ void gemm_phase(LAS unsigned char* lds, const bf16* gA, const bf16* gBt, const Sched& S, const Epi& E, const int wid) {
;     ...
;         if (!has_next) break;
; #pragma unroll
;         for (int a = 0; a < 2; ++a)
; #pragma unroll
;             for (int b = 0; b < 2; ++b)
; #pragma unroll
;                 for (int m = 0; m < 4; ++m)
; #pragma unroll
;                     for (int n = 0; n < 2; ++n) acc[a][b][m][n] = (f32x4){0.f, 0.f, 0.f, 0.f};
;         cur = nxt; cA = nA; cB = nB; ++ui;
;         if constexpr (ALIGN_EPI) { if (wr == 1) PG8_BAR; }
;     }
.Lp5b_skip:
	s_cbranch_vccnz .LBB0_1283
	s_andn2_b64 vcc, exec, s[10:11]
	s_cbranch_vccnz .LBB0_1282
	s_barrier
	s_branch .LBB0_1282
